# e18: chunk-state raw LDS ring 3 slots, LDS-DMA 3 steps ahead, loop wait vmcnt(4)
# speedup vs baseline: 1.0118x; 1.0040x over previous
; #define LAS __attribute__((address_space(3)))
; __device__ __forceinline__ float h2f(unsigned short u) { return (float)__builtin_bit_cast(_Float16, u); }
; #define LDS_WAIT() asm volatile("s_waitcnt lgkmcnt(0)" ::: "memory")
; __device__ __forceinline__ void hgrn_prep64(char* lds, int s, int w, int kc, int tq, float& gsum, bf16x8 (&vf)[2]) {
;     const int buf = s & 1; const char* raw = lds + buf * 49152; char* KDT = lds + 98304 + buf * 16384; float* DL = (float*)(lds + 131072 + buf * 512);
;     const int ch = 16 * w + kc;
;     float lf[2][8];
; #pragma unroll
;     for (int hf = 0; hf < 2; ++hf)
; #pragma unroll
;         for (int jj = 0; jj < 8; ++jj) { const int t = 32 * hf + 8 * tq + jj; lf[hf][jj] = h2f(*(const unsigned short*)(raw + (t * 128 + ch) * 2));
;             vf[hf][jj] = (short)*(const unsigned short*)(raw + 32768 + (t * 128 + ch) * 2); }
; __device__ __forceinline__ void hgrn_state_item64(const float* __restrict__ LOGF, const bf16* __restrict__ V, int row0, int nsteps, int h, bf16* __restrict__ Sout, float* __restrict__ Dout, char* lds) {
;     ...
;     const char* glf = (const char*)((const unsigned short*)LOGF + (size_t)(row0 + 8 * w + (lane >> 4)) * D + h * 128 + 8 * (lane & 15));
;     const char* gv = (const char*)(V + (size_t)(row0 + 8 * w + (lane >> 4)) * D + h * 128 + 8 * (lane & 15));
;     LAS char* ll = (LAS char*)lds;
;     ...
;     bf16x8 vf_cur[2], vf_nxt[2];
;     HG_DMA(0, 0); if (1 < nsteps) HG_DMA(1, 1);
;     asm volatile("s_waitcnt vmcnt(0)" ::: "memory"); __builtin_amdgcn_s_barrier(); asm volatile("" ::: "memory");
;     hgrn_prep64(lds, 0, w, kc, tq, gsum, vf_cur);
;     LDS_WAIT(); __builtin_amdgcn_s_barrier(); asm volatile("" ::: "memory");
.LBB0_2170:
	v_mov_b32_e32 v13, v0
	s_ashr_i32 s47, s46, 4
	s_lshl_b32 s4, s47, 10
	v_readfirstlane_b32 s5, v13
	s_ashr_i32 s6, s5, 6
	v_bfe_u32 v53, v13, 4, 2
	s_lshl_b32 s5, s6, 3
	v_or_b32_e32 v2, s4, v53
	v_add_u32_e32 v4, s5, v2
	v_ashrrev_i32_e32 v5, 31, v4
	s_and_b32 s19, s46, 15
	v_lshlrev_b64 v[4:5], 12, v[4:5]
	v_and_b32_e32 v56, 15, v13
	v_lshl_add_u64 v[6:7], s[12:13], 0, v[4:5]
	s_lshl_b32 s10, s19, 8
	v_lshl_add_u64 v[4:5], s[2:3], 0, v[4:5]
	s_lshl_b32 s7, s6, 11
	v_lshl_add_u64 v[6:7], v[6:7], 0, s[10:11]
	v_lshlrev_b32_e32 v2, 4, v56
	v_lshl_add_u64 v[4:5], v[4:5], 0, s[10:11]
	s_add_i32 s10, s7, 0
	v_lshl_add_u64 v[6:7], v[6:7], 0, v[2:3]
	s_mov_b32 m0, s10
	s_mov_b64 s[8:9], 0x4000
	global_load_lds_dwordx4 v[6:7], off
	v_lshl_add_u64 v[8:9], v[6:7], 0, s[8:9]
	s_add_i32 m0, s10, 0x400
	v_lshl_add_u64 v[4:5], v[4:5], 0, v[2:3]
	global_load_lds_dwordx4 v[8:9], off
	s_add_i32 m0, s10, 0xc000
	v_lshl_add_u64 v[8:9], v[4:5], 0, s[8:9]
	global_load_lds_dwordx4 v[4:5], off
	s_add_i32 m0, s10, 0xc400
	s_mov_b64 s[8:9], 0x44000
	global_load_lds_dwordx4 v[8:9], off
	s_add_i32 m0, s10, 0x4000
	v_lshl_add_u64 v[8:9], v[6:7], 0, s[60:61]
	global_load_lds_dwordx4 v[8:9], off
	v_lshl_add_u64 v[8:9], v[6:7], 0, s[8:9]
	s_add_i32 m0, s10, 0x4400
	s_lshl_b32 s18, s6, 4
	global_load_lds_dwordx4 v[8:9], off
	s_add_i32 m0, s10, 0x10000
	v_lshl_add_u64 v[8:9], v[4:5], 0, s[60:61]
	global_load_lds_dwordx4 v[8:9], off
	v_lshl_add_u64 v[8:9], v[4:5], 0, s[8:9]
	s_add_i32 m0, s10, 0x10400
	v_or_b32_e32 v52, s18, v56
	global_load_lds_dwordx4 v[8:9], off
	s_mov_b64 s[8:9], 0x80000
	v_lshl_add_u64 v[8:9], v[6:7], 0, s[8:9]
	s_add_i32 m0, s10, 0x8000
	s_mov_b64 s[8:9], 0x84000
	global_load_lds_dwordx4 v[8:9], off
	v_lshl_add_u64 v[8:9], v[6:7], 0, s[8:9]
	s_add_i32 m0, s10, 0x8400
	s_mov_b64 s[8:9], 0x80000
	global_load_lds_dwordx4 v[8:9], off
	v_lshl_add_u64 v[8:9], v[4:5], 0, s[8:9]
	s_add_i32 m0, s10, 0x14000
	s_mov_b64 s[8:9], 0x84000
	global_load_lds_dwordx4 v[8:9], off
	v_lshl_add_u64 v[8:9], v[4:5], 0, s[8:9]
	s_add_i32 m0, s10, 0x14400
	s_nop 0
	global_load_lds_dwordx4 v[8:9], off
	v_lshlrev_b32_e32 v4, 11, v53
	v_lshlrev_b32_e32 v5, 1, v52
	s_waitcnt vmcnt(4)
	s_barrier
	v_add3_u32 v57, v5, v4, 0
	ds_read_u16 v4, v57
	ds_read_u16 v5, v57 offset:256
	ds_read_u16 v6, v57 offset:512
	ds_read_u16 v7, v57 offset:768
	ds_read_u16 v8, v57 offset:1024
	ds_read_u16 v9, v57 offset:1280
	ds_read_u16 v10, v57 offset:1536
	ds_read_u16 v11, v57 offset:1792
	s_waitcnt lgkmcnt(0)
	v_cvt_f32_f16_e32 v46, v4
	v_cvt_f32_f16_e32 v48, v5
	v_cvt_f32_f16_e32 v45, v6
	v_cvt_f32_f16_e32 v40, v7
	v_cvt_f32_f16_e32 v30, v11
	ds_read_u16 v14, v57 offset:49152
	ds_read_u16 v15, v57 offset:49408
	ds_read_u16 v16, v57 offset:49664
	ds_read_u16 v17, v57 offset:49920
	ds_read_u16 v18, v57 offset:50176
	ds_read_u16 v19, v57 offset:50432
	ds_read_u16 v20, v57 offset:50688
	ds_read_u16 v21, v57 offset:50944
	ds_read_u16 v11, v57 offset:8192
	ds_read_u16 v12, v57 offset:8448
	ds_read_u16 v32, v57 offset:8704
	ds_read_u16 v34, v57 offset:8960
	ds_read_u16 v35, v57 offset:9216
	ds_read_u16 v36, v57 offset:9472
	ds_read_u16 v44, v57 offset:9728
	ds_read_u16 v47, v57 offset:9984
	ds_read_u16 v22, v57 offset:57344
	ds_read_u16 v23, v57 offset:57600
	ds_read_u16 v24, v57 offset:57856
	ds_read_u16 v25, v57 offset:58112
	ds_read_u16 v26, v57 offset:58368
	ds_read_u16 v27, v57 offset:58624
	ds_read_u16 v28, v57 offset:58880
	ds_read_u16 v29, v57 offset:59136
	v_cvt_f32_f16_e32 v38, v8
	v_cvt_f32_f16_e32 v6, v9
	v_add_f32_e32 v49, v46, v48
	v_cvt_f32_f16_e32 v4, v10
	v_add_f32_e32 v42, v49, v45
	v_add_f32_e32 v41, v42, v40
	v_add_f32_e32 v39, v41, v38
	v_add_f32_e32 v33, v39, v6
	v_add_f32_e32 v5, v33, v4
	v_add_f32_e32 v31, v5, v30
	v_mov_b32_e32 v9, v31
	v_mov_b32_e32 v7, v31
	s_nop 1
	v_permlane16_swap_b32_e32 v9, v7
	v_add_f32_e32 v8, v9, v7
	v_mov_b32_e32 v10, v8
	s_nop 1
	v_permlane32_swap_b32_e32 v8, v10
	v_cmp_lt_i32_e32 vcc, 0, v53
	v_mov_b32_e32 v7, 0
	s_and_saveexec_b64 s[20:21], vcc
	s_cbranch_execz .LBB0_2176
	v_cmp_ne_u32_e32 vcc, 1, v53
	s_and_saveexec_b64 s[6:7], vcc
	s_xor_b64 s[36:37], exec, s[6:7]
	v_add_f32_e32 v7, v9, v8
	v_cmp_eq_u32_e32 vcc, 2, v53
	s_nop 1
	v_cndmask_b32_e32 v7, v7, v8, vcc
	s_andn2_saveexec_b64 s[36:37], s[36:37]
	v_mov_b32_e32 v7, v9
	s_or_b64 exec, exec, s[36:37]

; __device__ __forceinline__ unsigned cvt_pk_bf16(float lo, float hi) { unsigned r; asm volatile("v_cvt_pk_bf16_f32 %0, %1, %2" : "=v"(r) : "v"(lo), "v"(hi)); return r; }
; #define LDS_WAIT() asm volatile("s_waitcnt lgkmcnt(0)" ::: "memory")
; __device__ __forceinline__ void hgrn_prep64(char* lds, int s, int w, int kc, int tq, float& gsum, bf16x8 (&vf)[2]) {
;     ...
;     const float R0 = c[0][7], R1 = c[1][7];
;     float P0, T0, p1_, t1_; row_prefix4(R0, tq, P0, T0); row_prefix4(R1, tq, p1_, t1_);
;     const float P1 = T0 + p1_, glast = T0 + t1_;
; #pragma unroll
;     for (int hf = 0; hf < 2; ++hf) { const float P = hf ? P1 : P0; float kd[8];
; #pragma unroll
;         for (int jj = 0; jj < 8; ++jj) kd[jj] = (1.f - __builtin_amdgcn_exp2f(lf[hf][jj])) * __builtin_amdgcn_exp2f(glast - (P + c[hf][jj]));
;         u32x4 kw; kw.x = cvt_pk_bf16(kd[0], kd[1]); kw.y = cvt_pk_bf16(kd[2], kd[3]); kw.z = cvt_pk_bf16(kd[4], kd[5]); kw.w = cvt_pk_bf16(kd[6], kd[7]);
;         *(u32x4*)(KDT + ch * 128 + (((4 * hf + tq) ^ (ch & 7)) << 4)) = kw; }
;     DL[ch] = __builtin_amdgcn_exp2f(glast);
;     gsum += glast;
; __device__ __forceinline__ void hgrn_state_item64(const float* __restrict__ LOGF, const bf16* __restrict__ V, int row0, int nsteps, int h, bf16* __restrict__ Sout, float* __restrict__ Dout, char* lds) {
;     ...
;     HG_DMA(0, 0); if (1 < nsteps) HG_DMA(1, 1);
;     asm volatile("s_waitcnt vmcnt(0)" ::: "memory"); __builtin_amdgcn_s_barrier(); asm volatile("" ::: "memory");
;     hgrn_prep64(lds, 0, w, kc, tq, gsum, vf_cur);
;     LDS_WAIT(); __builtin_amdgcn_s_barrier(); asm volatile("" ::: "memory");
; #pragma unroll 1
;     for (int s = 0; s < nsteps; ++s) {
;         if (s + 2 < nsteps) HG_DMA(s + 2, s & 1);
.LBB0_2182:
	s_or_b64 exec, exec, s[20:21]
	v_pk_add_f32 v[8:9], v[8:9], v[10:11]
	v_exp_f32_e32 v60, v6
	v_exp_f32_e32 v64, v4
	v_mov_b32_e32 v4, v8
	v_mov_b32_e32 v6, v9
	v_add_f32_e32 v10, v8, v59
	v_exp_f32_e32 v11, v46
	v_add_f32_e32 v46, v7, v46
	v_pk_add_f32 v[8:9], v[4:5], v[6:7]
	v_add_f32_e32 v6, v33, v7
	v_sub_f32_e32 v4, v8, v46
	v_exp_f32_e32 v4, v4
	v_add_f32_e32 v49, v49, v7
	v_add_f32_e32 v42, v42, v7
	v_add_f32_e32 v41, v41, v7
	v_add_f32_e32 v39, v39, v7
	v_sub_f32_e32 v6, v8, v6
	v_add_f32_e32 v7, v31, v7
	v_sub_f32_e32 v11, 1.0, v11
	v_exp_f32_e32 v6, v6
	v_sub_f32_e32 v9, v8, v9
	v_exp_f32_e32 v30, v30
	v_sub_f32_e32 v7, v8, v7
	v_exp_f32_e32 v48, v48
	v_exp_f32_e32 v45, v45
	v_exp_f32_e32 v40, v40
	v_exp_f32_e32 v38, v38
	v_mul_f32_e32 v4, v11, v4
	v_sub_f32_e32 v11, v8, v49
	v_sub_f32_e32 v42, v8, v42
	v_sub_f32_e32 v41, v8, v41
	v_sub_f32_e32 v39, v8, v39
	v_exp_f32_e32 v9, v9
	v_exp_f32_e32 v7, v7
	v_exp_f32_e32 v11, v11
	v_exp_f32_e32 v42, v42
	v_exp_f32_e32 v41, v41
	v_exp_f32_e32 v39, v39
	v_sub_f32_e32 v5, 1.0, v60
	v_sub_f32_e32 v33, 1.0, v64
	v_mul_f32_e32 v6, v5, v6
	v_sub_f32_e32 v5, 1.0, v30
	v_sub_f32_e32 v48, 1.0, v48
	v_sub_f32_e32 v45, 1.0, v45
	v_sub_f32_e32 v40, 1.0, v40
	v_sub_f32_e32 v38, 1.0, v38
	v_mul_f32_e32 v9, v33, v9
	v_mul_f32_e32 v7, v5, v7
	s_add_i32 s7, 0, 0x18000
	v_mul_f32_e32 v11, v48, v11
	v_mul_f32_e32 v42, v45, v42
	v_mul_f32_e32 v40, v40, v41
	v_mul_f32_e32 v38, v38, v39
	v_cvt_pk_bf16_f32 v4, v4, v11
	v_cvt_pk_bf16_f32 v5, v42, v40
	v_cvt_pk_bf16_f32 v6, v38, v6
	v_cvt_pk_bf16_f32 v7, v9, v7
	v_bitop3_b32 v9, v53, v13, 7 bitop3:0x78
	v_lshl_add_u32 v59, v52, 7, s7
	v_lshlrev_b32_e32 v60, 4, v9
	v_add_u32_e32 v9, v59, v60
	ds_write_b128 v9, v[4:7]
	v_add_f32_e32 v5, v10, v61
	v_exp_f32_e32 v4, v61
	v_sub_f32_e32 v5, v8, v5
	v_add_f32_e32 v7, v62, v10
	v_exp_f32_e32 v5, v5
	v_exp_f32_e32 v6, v58
	v_sub_f32_e32 v7, v8, v7
	v_exp_f32_e32 v7, v7
	v_sub_f32_e32 v4, 1.0, v4
	v_mul_f32_e32 v4, v4, v5
	v_sub_f32_e32 v5, 1.0, v6
	v_mul_f32_e32 v5, v5, v7
	v_add_f32_e32 v7, v55, v10
	v_exp_f32_e32 v6, v51
	v_sub_f32_e32 v7, v8, v7
	v_add_f32_e32 v11, v54, v10
	v_exp_f32_e32 v7, v7
	v_exp_f32_e32 v9, v50
	v_sub_f32_e32 v11, v8, v11
	v_exp_f32_e32 v11, v11
	v_sub_f32_e32 v6, 1.0, v6
	v_mul_f32_e32 v6, v6, v7
	v_sub_f32_e32 v7, 1.0, v9
	v_mul_f32_e32 v7, v7, v11
	v_add_f32_e32 v11, v47, v10
	v_exp_f32_e32 v9, v43
	v_sub_f32_e32 v11, v8, v11
	v_add_f32_e32 v30, v44, v10
	v_and_b32_e32 v63, 7, v13
	v_exp_f32_e32 v11, v11
	v_exp_f32_e32 v13, v37
	v_sub_f32_e32 v30, v8, v30
	v_exp_f32_e32 v30, v30
	v_sub_f32_e32 v9, 1.0, v9
	v_mul_f32_e32 v9, v9, v11
	v_sub_f32_e32 v11, 1.0, v13
	v_mul_f32_e32 v11, v11, v30
	v_add_f32_e32 v30, v36, v10
	v_exp_f32_e32 v13, v34
	v_sub_f32_e32 v30, v8, v30
	v_add_f32_e32 v10, v35, v10
	v_exp_f32_e32 v30, v30
	v_exp_f32_e32 v31, v32
	v_sub_f32_e32 v10, v8, v10
	v_exp_f32_e32 v10, v10
	v_sub_f32_e32 v13, 1.0, v13
	v_mul_f32_e32 v13, v13, v30
	v_sub_f32_e32 v30, 1.0, v31
	v_cvt_pk_bf16_f32 v4, v4, v5
	v_cvt_pk_bf16_f32 v5, v6, v7
	v_cvt_pk_bf16_f32 v6, v9, v11
	v_bitop3_b32 v9, v53, v63, 4 bitop3:0x36
	v_mul_f32_e32 v10, v30, v10
	v_lshlrev_b32_e32 v61, 4, v9
	v_cvt_pk_bf16_f32 v7, v13, v10
	v_add_u32_e32 v9, v59, v61
	v_exp_f32_e32 v10, v8
	s_add_i32 s4, s4, s5
	ds_write_b128 v9, v[4:7]
	v_add_u32_e32 v4, s4, v53
	s_and_b32 s6, s40, 15
	s_add_i32 s8, 0, 0x20000
	v_ashrrev_i32_e32 v5, 31, v4
	s_lshl_b32 s6, s6, 8
	v_lshl_add_u32 v62, v52, 2, s8
	v_lshlrev_b64 v[4:5], 12, v[4:5]
	ds_write_b32 v62, v10
	v_or3_b32 v4, v4, s6, v2
	v_add_f32_e32 v58, 0, v8
	s_waitcnt lgkmcnt(0)
	s_barrier
	v_lshl_add_u64 v[54:55], s[0:1], 0, v[4:5]
	v_mov_b32_e32 v4, v3
	v_mov_b32_e32 v5, v3
	v_mov_b32_e32 v6, v3
	v_mov_b32_e32 v7, v3
	v_mov_b32_e32 v8, v3
	v_mov_b32_e32 v9, v3
	v_mov_b32_e32 v2, v3
	v_mov_b64_e32 v[10:11], v[8:9]
	v_lshl_add_u32 v63, v53, 4, s8
	v_lshl_add_u32 v64, v56, 7, s7
	v_cmp_eq_u32_e32 vcc, 2, v53
	v_perm_b32 v44, v15, v14, s35
	v_perm_b32 v45, v17, v16, s35
	v_perm_b32 v46, v19, v18, s35
	v_perm_b32 v47, v21, v20, s35
	v_perm_b32 v48, v23, v22, s35
	v_perm_b32 v49, v25, v24, s35
	v_perm_b32 v50, v27, v26, s35
	v_perm_b32 v51, v29, v28, s35
	s_mov_b32 s4, 0
	s_mov_b64 s[20:21], 0
	v_mov_b64_e32 v[8:9], v[6:7]
	v_mov_b64_e32 v[6:7], v[4:5]
	v_mov_b64_e32 v[4:5], v[2:3]
	v_mov_b32_e32 v13, v12
	v_mov_b32_e32 v14, v12
	v_mov_b32_e32 v15, v12
	v_mov_b32_e32 v40, v12
	v_mov_b32_e32 v41, v12
	v_mov_b32_e32 v42, v12
	v_mov_b32_e32 v43, v12
	v_mov_b32_e32 v36, v12
	v_mov_b32_e32 v37, v12
	v_mov_b32_e32 v38, v12
	v_mov_b32_e32 v39, v12
	v_mov_b32_e32 v32, v12
	v_mov_b32_e32 v33, v12
	v_mov_b32_e32 v34, v12
	v_mov_b32_e32 v35, v12
	v_mov_b32_e32 v28, v12
	v_mov_b32_e32 v29, v12
	v_mov_b32_e32 v30, v12
	v_mov_b32_e32 v31, v12
	v_mov_b32_e32 v24, v12
	v_mov_b32_e32 v25, v12
	v_mov_b32_e32 v26, v12
	v_mov_b32_e32 v27, v12
	v_mov_b32_e32 v20, v12
	v_mov_b32_e32 v21, v12
	v_mov_b32_e32 v22, v12
	v_mov_b32_e32 v23, v12
	v_mov_b32_e32 v16, v12
	v_mov_b32_e32 v17, v12
	v_mov_b32_e32 v18, v12
	v_mov_b32_e32 v19, v12
	s_cmp_gt_u32 s4, 12
	s_cbranch_scc1 .LBB0_2185
	s_branch .LBB0_2184
.LBB0_2183:
	v_mov_b32_e32 v44, v4
	v_mov_b32_e32 v45, v5
	v_mov_b32_e32 v46, v6
	v_mov_b32_e32 v47, v7
	v_mov_b32_e32 v48, v8
	v_mov_b32_e32 v49, v9
	v_mov_b32_e32 v50, v10
	v_mov_b32_e32 v51, v11
	s_cmp_gt_u32 s4, 12
	s_cbranch_scc1 .LBB0_2185
; __device__ __forceinline__ void hgrn_prep64(char* lds, int s, int w, int kc, int tq, float& gsum, bf16x8 (&vf)[2]) {
;     const int buf = s & 1; const char* raw = lds + buf * 49152; char* KDT = lds + 98304 + buf * 16384; float* DL = (float*)(lds + 131072 + buf * 512);
;     const int ch = 16 * w + kc;
; __device__ __forceinline__ void hgrn_mma64(char* lds, int s, int kc, int tq, const bf16x8 (&vf)[2], f32x4 (&S)[8]) {
;     const int buf = s & 1; const char* KDT = lds + 98304 + buf * 16384; const float* DL = (const float*)(lds + 131072 + buf * 512);
; #pragma unroll
;     for (int kb = 0; kb < 8; ++kb) { const f32x4 dlv = *(const f32x4*)(DL + 16 * kb + 4 * tq); const int kr = 16 * kb + kc;
;         const bf16x8 k0 = *(const bf16x8*)(KDT + kr * 128 + ((tq ^ (kr & 7)) << 4)), k1 = *(const bf16x8*)(KDT + kr * 128 + (((4 + tq) ^ (kr & 7)) << 4));
;         f32x4 acc = S[kb] * dlv;
;         acc = __builtin_amdgcn_mfma_f32_16x16x32_bf16(k0, vf[0], acc, 0, 0, 0);
;         S[kb] = __builtin_amdgcn_mfma_f32_16x16x32_bf16(k1, vf[1], acc, 0, 0, 0); }
; }
; __device__ __forceinline__ void hgrn_state_item64(const float* __restrict__ LOGF, const bf16* __restrict__ V, int row0, int nsteps, int h, bf16* __restrict__ Sout, float* __restrict__ Dout, char* lds) {
;     const int tid = opaque_tid(), w = __builtin_amdgcn_readfirstlane(tid >> 6), lane = tid & 63, kc = lane & 15, tq = lane >> 4;
;     f32x4 S[8];
; #pragma unroll
;     for (int kb = 0; kb < 8; ++kb) S[kb] = (f32x4){0.f, 0.f, 0.f, 0.f};
;     float gsum = 0.f;
;     const char* glf = (const char*)((const unsigned short*)LOGF + (size_t)(row0 + 8 * w + (lane >> 4)) * D + h * 128 + 8 * (lane & 15));
;     const char* gv = (const char*)(V + (size_t)(row0 + 8 * w + (lane >> 4)) * D + h * 128 + 8 * (lane & 15));
;     LAS char* ll = (LAS char*)lds;
;     ...
;     bf16x8 vf_cur[2], vf_nxt[2];
;     HG_DMA(0, 0); if (1 < nsteps) HG_DMA(1, 1);
;     asm volatile("s_waitcnt vmcnt(0)" ::: "memory"); __builtin_amdgcn_s_barrier(); asm volatile("" ::: "memory");
;     hgrn_prep64(lds, 0, w, kc, tq, gsum, vf_cur);
;     LDS_WAIT(); __builtin_amdgcn_s_barrier(); asm volatile("" ::: "memory");
; #pragma unroll 1
;     for (int s = 0; s < nsteps; ++s) {
;         if (s + 2 < nsteps) HG_DMA(s + 2, s & 1);
;         hgrn_mma64(lds, s, kc, tq, vf_cur, S);
;         if (s + 1 < nsteps) hgrn_prep64(lds, s + 1, w, kc, tq, gsum, vf_nxt);
.LBB0_2184:
	s_mul_i32 s5, s4, 11
	s_lshr_b32 s5, s5, 5
	s_mul_i32 s5, s5, 3
	s_sub_i32 s5, s4, s5
	s_lshl_b32 s5, s5, 14
	s_add_i32 s5, s10, s5
	v_lshl_add_u64 v[66:67], v[54:55], 0, s[20:21]
	s_mov_b64 s[6:7], 0x285c0000
	v_lshl_add_u64 v[68:69], v[66:67], 0, s[6:7]
	s_mov_b32 m0, s5
	s_mov_b64 s[6:7], 0x285c4000
	global_load_lds_dwordx4 v[68:69], off
	v_lshl_add_u64 v[68:69], v[66:67], 0, s[6:7]
	s_add_i32 m0, s5, 0x400
	s_mov_b64 s[6:7], 0x307c0000
	global_load_lds_dwordx4 v[68:69], off
	s_add_i32 m0, s5, 0xc000
	v_lshl_add_u64 v[68:69], v[66:67], 0, s[6:7]
	s_mov_b64 s[6:7], 0x307c4000
	global_load_lds_dwordx4 v[68:69], off
	v_lshl_add_u64 v[66:67], v[66:67], 0, s[6:7]
	s_add_i32 m0, s5, 0xc400
	s_nop 0
	global_load_lds_dwordx4 v[66:67], off
.LBB0_2185:
	s_and_b32 s5, s4, 1
	v_lshl_add_u32 v65, s5, 14, v64
	v_add_u32_e32 v78, v65, v60
	ds_read_b128 v[70:73], v78
	v_lshl_add_u32 v2, s5, 9, v63
	ds_read_b128 v[66:69], v2
	v_add_u32_e32 v65, v65, v61
	ds_read_b128 v[74:77], v65
	s_add_i32 s4, s4, 1
	s_cmp_eq_u32 s20, 0x3c0000
	s_waitcnt lgkmcnt(0)
	v_pk_mul_f32 v[12:13], v[12:13], v[66:67]
	v_pk_mul_f32 v[14:15], v[14:15], v[68:69]
	s_nop 1
	v_mfma_f32_16x16x32_bf16 v[12:15], v[70:73], v[44:47], v[12:15]
	v_mfma_f32_16x16x32_bf16 v[12:15], v[74:77], v[48:51], v[12:15]
	ds_read_b128 v[66:69], v2 offset:64
	ds_read_b128 v[70:73], v78 offset:2048
	ds_read_b128 v[74:77], v65 offset:2048
	s_waitcnt lgkmcnt(0)
	v_pk_mul_f32 v[40:41], v[40:41], v[66:67]
	v_pk_mul_f32 v[42:43], v[42:43], v[68:69]
	s_nop 1
	v_mfma_f32_16x16x32_bf16 v[40:43], v[70:73], v[44:47], v[40:43]
	v_mfma_f32_16x16x32_bf16 v[40:43], v[74:77], v[48:51], v[40:43]
	ds_read_b128 v[66:69], v2 offset:128
	ds_read_b128 v[70:73], v78 offset:4096
	ds_read_b128 v[74:77], v65 offset:4096
	s_waitcnt lgkmcnt(0)
	v_pk_mul_f32 v[36:37], v[36:37], v[66:67]
	v_pk_mul_f32 v[38:39], v[38:39], v[68:69]
	s_nop 1
	v_mfma_f32_16x16x32_bf16 v[36:39], v[70:73], v[44:47], v[36:39]
	v_mfma_f32_16x16x32_bf16 v[36:39], v[74:77], v[48:51], v[36:39]
	ds_read_b128 v[66:69], v2 offset:192
	ds_read_b128 v[70:73], v78 offset:6144
	ds_read_b128 v[74:77], v65 offset:6144
	s_waitcnt lgkmcnt(0)
	v_pk_mul_f32 v[32:33], v[32:33], v[66:67]
	v_pk_mul_f32 v[34:35], v[34:35], v[68:69]
	s_nop 1
	v_mfma_f32_16x16x32_bf16 v[32:35], v[70:73], v[44:47], v[32:35]
	v_mfma_f32_16x16x32_bf16 v[32:35], v[74:77], v[48:51], v[32:35]
	ds_read_b128 v[66:69], v2 offset:256
	ds_read_b128 v[70:73], v78 offset:8192
	ds_read_b128 v[74:77], v65 offset:8192
	s_waitcnt lgkmcnt(0)
	v_pk_mul_f32 v[28:29], v[28:29], v[66:67]
	v_pk_mul_f32 v[30:31], v[30:31], v[68:69]
	s_nop 1
	v_mfma_f32_16x16x32_bf16 v[28:31], v[70:73], v[44:47], v[28:31]
	v_mfma_f32_16x16x32_bf16 v[28:31], v[74:77], v[48:51], v[28:31]
	ds_read_b128 v[66:69], v2 offset:320
	ds_read_b128 v[70:73], v78 offset:10240
	ds_read_b128 v[74:77], v65 offset:10240
	s_waitcnt lgkmcnt(0)
	v_pk_mul_f32 v[24:25], v[24:25], v[66:67]
	v_pk_mul_f32 v[26:27], v[26:27], v[68:69]
	s_nop 1
	v_mfma_f32_16x16x32_bf16 v[24:27], v[70:73], v[44:47], v[24:27]
	v_mfma_f32_16x16x32_bf16 v[24:27], v[74:77], v[48:51], v[24:27]
	ds_read_b128 v[66:69], v2 offset:384
	ds_read_b128 v[70:73], v78 offset:12288
	ds_read_b128 v[74:77], v65 offset:12288
	s_waitcnt lgkmcnt(0)
	v_pk_mul_f32 v[20:21], v[20:21], v[66:67]
	v_pk_mul_f32 v[22:23], v[22:23], v[68:69]
	s_nop 1
	v_mfma_f32_16x16x32_bf16 v[20:23], v[70:73], v[44:47], v[20:23]
	v_mfma_f32_16x16x32_bf16 v[20:23], v[74:77], v[48:51], v[20:23]
	ds_read_b128 v[66:69], v2 offset:448
	ds_read_b128 v[70:73], v78 offset:14336
	ds_read_b128 v[74:77], v65 offset:14336
	s_waitcnt lgkmcnt(0)
	v_pk_mul_f32 v[16:17], v[16:17], v[66:67]
	v_pk_mul_f32 v[18:19], v[18:19], v[68:69]
	s_nop 1
	v_mfma_f32_16x16x32_bf16 v[16:19], v[70:73], v[44:47], v[16:19]
	v_mfma_f32_16x16x32_bf16 v[16:19], v[74:77], v[48:51], v[16:19]
	s_cbranch_scc1 .LBB0_2199
	s_and_b32 s5, s4, 1
	s_mul_i32 s6, s4, 11
	s_lshr_b32 s6, s6, 5
	s_mul_i32 s6, s6, 3
	s_sub_i32 s6, s4, s6
	s_lshl_b32 s6, s6, 14
	v_add_u32_e32 v47, s6, v57
	ds_read_u16 v2, v47
	ds_read_u16 v4, v47 offset:256
	ds_read_u16 v5, v47 offset:512
	ds_read_u16 v6, v47 offset:768
	ds_read_u16 v7, v47 offset:1024
	ds_read_u16 v8, v47 offset:1280
	ds_read_u16 v9, v47 offset:1536
	ds_read_u16 v10, v47 offset:1792
	s_waitcnt lgkmcnt(0)
	v_cvt_f32_f16_e32 v80, v2
	v_cvt_f32_f16_e32 v82, v4
	v_cvt_f32_f16_e32 v79, v5
	v_cvt_f32_f16_e32 v74, v6
	v_cvt_f32_f16_e32 v71, v7
	v_cvt_f32_f16_e32 v46, v8
	v_add_f32_e32 v83, v80, v82
	v_cvt_f32_f16_e32 v44, v9
	v_add_f32_e32 v76, v83, v79
	v_cvt_f32_f16_e32 v2, v10
	v_add_f32_e32 v75, v76, v74
	v_add_f32_e32 v73, v75, v71
	v_add_f32_e32 v67, v73, v46
	v_add_f32_e32 v45, v67, v44
	v_add_f32_e32 v65, v45, v2
	v_mov_b32_e32 v49, v65
	v_mov_b32_e32 v4, v65
	s_nop 1
	v_permlane16_swap_b32_e32 v49, v4
	v_add_f32_e32 v48, v49, v4
	ds_read_u16 v4, v47 offset:49152
	ds_read_u16 v91, v47 offset:49408
	ds_read_u16 v5, v47 offset:49664
	ds_read_u16 v92, v47 offset:49920
	ds_read_u16 v6, v47 offset:50176
	ds_read_u16 v93, v47 offset:50432
	ds_read_u16 v7, v47 offset:50688
	ds_read_u16 v94, v47 offset:50944
	ds_read_u16 v51, v47 offset:8192
	ds_read_u16 v66, v47 offset:8448
	ds_read_u16 v68, v47 offset:8704
	ds_read_u16 v69, v47 offset:8960
	ds_read_u16 v70, v47 offset:9216
	ds_read_u16 v72, v47 offset:9472
	ds_read_u16 v78, v47 offset:9728
	ds_read_u16 v81, v47 offset:9984
	ds_read_u16 v8, v47 offset:57344
	ds_read_u16 v95, v47 offset:57600
	ds_read_u16 v9, v47 offset:57856
	ds_read_u16 v96, v47 offset:58112
	ds_read_u16 v10, v47 offset:58368
	ds_read_u16 v97, v47 offset:58624
	ds_read_u16 v11, v47 offset:58880
	ds_read_u16 v98, v47 offset:59136
	v_mov_b32_e32 v50, v48
	s_nop 1
	v_permlane32_swap_b32_e32 v48, v50
	v_cmp_lt_i32_e64 s[38:39], 0, v53
	v_mov_b32_e32 v47, 0
	s_and_saveexec_b64 s[36:37], s[38:39]
	s_cbranch_execz .LBB0_2192
	v_cmp_ne_u32_e64 s[38:39], 1, v53
	s_and_saveexec_b64 s[6:7], s[38:39]
	s_xor_b64 s[38:39], exec, s[6:7]
	v_add_f32_e32 v47, v49, v48
	v_cndmask_b32_e32 v47, v47, v48, vcc
	s_andn2_saveexec_b64 s[38:39], s[38:39]
	v_mov_b32_e32 v47, v49
	s_or_b64 exec, exec, s[38:39]

; __device__ __forceinline__ void hgrn_state_item64(const float* __restrict__ LOGF, const bf16* __restrict__ V, int row0, int nsteps, int h, bf16* __restrict__ Sout, float* __restrict__ Dout, char* lds) {
;     ...
;     for (int s = 0; s < nsteps; ++s) {
;         if (s + 2 < nsteps) HG_DMA(s + 2, s & 1);
;         hgrn_mma64(lds, s, kc, tq, vf_cur, S);
;         if (s + 1 < nsteps) hgrn_prep64(lds, s + 1, w, kc, tq, gsum, vf_nxt);
;         asm volatile("s_waitcnt vmcnt(0) lgkmcnt(0)" ::: "memory"); __builtin_amdgcn_s_barrier(); asm volatile("" ::: "memory");
;         vf_cur[0] = vf_nxt[0]; vf_cur[1] = vf_nxt[1];
;     }
.LBB0_2199:
	s_cmp_gt_u32 s4, 13
	s_cbranch_scc1 .Lcs3_w0
	s_waitcnt vmcnt(4) lgkmcnt(0)
	s_branch .Lcs3_wd

; __device__ __forceinline__ unsigned cvt_pk_bf16(float lo, float hi) { unsigned r; asm volatile("v_cvt_pk_bf16_f32 %0, %1, %2" : "=v"(r) : "v"(lo), "v"(hi)); return r; }
; #define LDS_WAIT() asm volatile("s_waitcnt lgkmcnt(0)" ::: "memory")
; __device__ __forceinline__ void hgrn_state_item64(const float* __restrict__ LOGF, const bf16* __restrict__ V, int row0, int nsteps, int h, bf16* __restrict__ Sout, float* __restrict__ Dout, char* lds) {
;     ...
;         asm volatile("s_waitcnt vmcnt(0) lgkmcnt(0)" ::: "memory"); __builtin_amdgcn_s_barrier(); asm volatile("" ::: "memory");
;         vf_cur[0] = vf_nxt[0]; vf_cur[1] = vf_nxt[1];
;     }
;     ...
; #pragma unroll
;     for (int kb = 0; kb < 8; ++kb)
; #pragma unroll
;         for (int i = 0; i < 4; ++i) Sout[(size_t)(16 * kb + 4 * tq + i) * 128 + 16 * w + kc] = (bf16)(cvt_pk_bf16(S[kb][i], 0.f) & 0xffffu);
;     if (tq == 0) Dout[16 * w + kc] = __builtin_amdgcn_exp2f(gsum);
;     LDS_WAIT(); __builtin_amdgcn_s_barrier(); asm volatile("" ::: "memory");
.Lcs3_wd:
	s_barrier
	s_add_u32 s20, s20, 0x40000
	s_addc_u32 s21, s21, 0
	s_cmp_eq_u32 s20, 0x400000
	s_cbranch_scc0 .LBB0_2183
	s_lshl_b32 s4, s19, 4
	s_add_i32 s20, s4, s47
	s_ashr_i32 s21, s20, 31
	s_lshl_b64 s[4:5], s[20:21], 15
	s_add_u32 s6, s42, s4
	s_addc_u32 s7, s43, s5
	s_ashr_i32 s19, s18, 31
	s_lshl_b64 s[4:5], s[18:19], 1
	s_add_u32 s4, s6, s4
	s_addc_u32 s5, s7, s5
	v_lshlrev_b32_e32 v2, 1, v56
	v_lshl_add_u64 v[4:5], s[4:5], 0, v[2:3]
	v_lshlrev_b32_e32 v2, 10, v53
	v_cvt_pk_bf16_f32 v6, v12, v3
	v_lshl_add_u64 v[4:5], v[4:5], 0, v[2:3]
	global_store_short v[4:5], v6, off
	v_cvt_pk_bf16_f32 v2, v13, v3
	v_add_co_u32_e32 v6, vcc, s97, v4
	global_store_short v[4:5], v2, off offset:256
	v_cvt_pk_bf16_f32 v2, v14, v3
	s_nop 0
	v_addc_co_u32_e32 v7, vcc, 0, v5, vcc
	global_store_short v[4:5], v2, off offset:512
	v_cvt_pk_bf16_f32 v2, v15, v3
	v_add_co_u32_e32 v8, vcc, s75, v4
	global_store_short v[4:5], v2, off offset:768
	v_cvt_pk_bf16_f32 v2, v40, v3
	s_nop 0
	v_addc_co_u32_e32 v9, vcc, 0, v5, vcc
	global_store_short v[8:9], v2, off offset:-4096
	v_cvt_pk_bf16_f32 v2, v41, v3
	global_store_short v[6:7], v2, off offset:256
	v_cvt_pk_bf16_f32 v2, v42, v3
	global_store_short v[6:7], v2, off offset:512
	v_cvt_pk_bf16_f32 v2, v43, v3
	global_store_short v[6:7], v2, off offset:768
	v_cvt_pk_bf16_f32 v2, v36, v3
	s_movk_i32 s4, 0x3000
	global_store_short v[8:9], v2, off
	v_cvt_pk_bf16_f32 v2, v37, v3
	v_add_co_u32_e32 v6, vcc, s4, v4
	global_store_short v[8:9], v2, off offset:256
	v_cvt_pk_bf16_f32 v2, v38, v3
	s_nop 0
	v_addc_co_u32_e32 v7, vcc, 0, v5, vcc
	s_movk_i32 s4, 0x4000
	global_store_short v[8:9], v2, off offset:512
	v_cvt_pk_bf16_f32 v2, v39, v3
	global_store_short v[8:9], v2, off offset:768
	v_add_co_u32_e32 v8, vcc, s4, v4
	v_cvt_pk_bf16_f32 v2, v32, v3
	s_movk_i32 s4, 0x5000
	s_nop 0
	v_addc_co_u32_e32 v9, vcc, 0, v5, vcc
	global_store_short v[8:9], v2, off offset:-4096
	v_cvt_pk_bf16_f32 v2, v33, v3
	global_store_short v[6:7], v2, off offset:256
	v_cvt_pk_bf16_f32 v2, v34, v3
	global_store_short v[6:7], v2, off offset:512
	v_cvt_pk_bf16_f32 v2, v35, v3
	global_store_short v[6:7], v2, off offset:768
	v_cvt_pk_bf16_f32 v2, v28, v3
	global_store_short v[8:9], v2, off
	v_cvt_pk_bf16_f32 v2, v29, v3
	v_add_co_u32_e32 v6, vcc, s4, v4
	global_store_short v[8:9], v2, off offset:256
	v_cvt_pk_bf16_f32 v2, v30, v3
	s_nop 0
	v_addc_co_u32_e32 v7, vcc, 0, v5, vcc
	s_movk_i32 s4, 0x6000
	global_store_short v[8:9], v2, off offset:512
	v_cvt_pk_bf16_f32 v2, v31, v3
	global_store_short v[8:9], v2, off offset:768
	v_add_co_u32_e32 v8, vcc, s4, v4
	v_cvt_pk_bf16_f32 v2, v24, v3
	s_nop 1
	v_addc_co_u32_e32 v9, vcc, 0, v5, vcc
	global_store_short v[8:9], v2, off offset:-4096
	v_cvt_pk_bf16_f32 v2, v25, v3
	global_store_short v[6:7], v2, off offset:256
	v_cvt_pk_bf16_f32 v2, v26, v3
	global_store_short v[6:7], v2, off offset:512
	v_cvt_pk_bf16_f32 v2, v27, v3
	global_store_short v[6:7], v2, off offset:768
	v_cvt_pk_bf16_f32 v2, v20, v3
	global_store_short v[8:9], v2, off
	v_cvt_pk_bf16_f32 v2, v21, v3
	global_store_short v[8:9], v2, off offset:256
	v_cvt_pk_bf16_f32 v2, v22, v3
	global_store_short v[8:9], v2, off offset:512
	v_cvt_pk_bf16_f32 v2, v23, v3
	v_add_co_u32_e32 v4, vcc, 0x7000, v4
	global_store_short v[8:9], v2, off offset:768
	v_cvt_pk_bf16_f32 v2, v16, v3
	s_nop 0
	v_addc_co_u32_e32 v5, vcc, 0, v5, vcc
	global_store_short v[4:5], v2, off
	v_cvt_pk_bf16_f32 v2, v17, v3
	global_store_short v[4:5], v2, off offset:256
	v_cvt_pk_bf16_f32 v2, v18, v3
	v_cmp_eq_u32_e32 vcc, 0, v53
	global_store_short v[4:5], v2, off offset:512
	v_cvt_pk_bf16_f32 v2, v19, v3
	global_store_short v[4:5], v2, off offset:768
	s_and_saveexec_b64 s[18:19], vcc
	s_cbranch_execz .LBB0_2169
	s_lshl_b64 s[4:5], s[20:21], 9
	v_exp_f32_e32 v2, v58
	s_add_u32 s4, s44, s4
	s_addc_u32 s5, s45, s5
	v_ashrrev_i32_e32 v53, 31, v52
	v_lshl_add_u64 v[4:5], v[52:53], 2, s[4:5]
	global_store_dword v[4:5], v2, off
	s_branch .LBB0_2169
